# grid barrier: all workgroups wait on the top arrival counter itself (>= target), leaders arrive with a non-returning atomic; the separate generation words are no longer used
# baseline (speedup 1.0000x reference)
.LBB0_114:
	s_waitcnt lgkmcnt(0)
	v_mov_b32_e32 v2, 0x20160
	ds_read2_b32 v[4:5], v2 offset1:1
	ds_read_b32 v6, v2 offset:8
	v_readlane_b32 s100, v254, 8
	v_readlane_b32 s101, v254, 9
	v_mov_b32_e32 v3, 1
	v_mov_b32_e32 v11, 0
	v_mov_b32_e32 v8, s100
	v_mov_b32_e32 v9, s101
	global_atomic_add v10, v[8:9], v3, off sc0
	s_waitcnt lgkmcnt(0)
	v_add_u32_e32 v7, 1, v6
	ds_write_b32 v2, v7 offset:8
	v_mul_lo_u32 v4, v4, v7
	v_mul_lo_u32 v5, v5, v7
	s_waitcnt vmcnt(0)
	buffer_inv sc1
	v_add_u32_e32 v10, 1, v10
	v_cmp_eq_u32_e32 vcc, v10, v4
	v_readlane_b32 s100, v254, 12
	v_readlane_b32 s101, v254, 13
	s_nop 1
	v_mov_b32_e32 v8, s100
	v_mov_b32_e32 v9, s101
	s_cbranch_vccz .Lxb1_wait
	buffer_wbl2 sc1
	s_waitcnt vmcnt(0)
	global_atomic_add v[8:9], v3, off
.Lxb1_wait:
	global_load_dword v10, v[8:9], off sc1
	s_waitcnt vmcnt(0)
	v_cmp_ge_u32_e32 vcc, v10, v5
	s_cbranch_vccnz .Lxb1_fin
	v_add_u32_e32 v11, 1, v11
	v_and_b32_e32 v10, 0xff, v11
	v_cmp_eq_u32_e32 vcc, 0, v10
	s_cbranch_vccz .Lxb1_wait
	v_readlane_b32 s100, v253, 6
	v_readlane_b32 s101, v253, 7
	s_nop 1
	v_mov_b32_e32 v14, s100
	v_mov_b32_e32 v15, s101
	global_load_dword v10, v[14:15], off sc1
	s_waitcnt vmcnt(0)
	v_cmp_ne_u32_e32 vcc, 0, v10
	s_cbranch_vccnz .Lxb1_fin
	v_cmp_lt_u32_e32 vcc, 0x40000, v11
	s_cbranch_vccz .Lxb1_wait
	global_atomic_add v[14:15], v3, off

.LBB0_161:
	s_or_b64 exec, exec, s[18:19]
	s_cmp_lt_i32 s51, 3
	s_cbranch_scc1 .LBB0_215
	s_waitcnt vmcnt(0)
	s_barrier
	s_mov_b64 s[4:5], exec
	v_readlane_b32 s0, v253, 0
	v_readlane_b32 s1, v253, 1
	s_and_b64 s[0:1], s[4:5], s[0:1]
	s_mov_b64 exec, s[0:1]
	s_cbranch_execz .LBB0_214
	s_waitcnt lgkmcnt(0)
	v_mov_b32_e32 v2, 0x20160
	ds_read2_b32 v[4:5], v2 offset1:1
	ds_read_b32 v6, v2 offset:8
	v_readlane_b32 s100, v254, 8
	v_readlane_b32 s101, v254, 9
	v_mov_b32_e32 v3, 1
	v_mov_b32_e32 v11, 0
	v_mov_b32_e32 v8, s100
	v_mov_b32_e32 v9, s101
	global_atomic_add v10, v[8:9], v3, off sc0
	s_waitcnt lgkmcnt(0)
	v_add_u32_e32 v7, 1, v6
	ds_write_b32 v2, v7 offset:8
	v_mul_lo_u32 v4, v4, v7
	v_mul_lo_u32 v5, v5, v7
	s_waitcnt vmcnt(0)
	buffer_inv sc1
	v_add_u32_e32 v10, 1, v10
	v_cmp_eq_u32_e32 vcc, v10, v4
	v_readlane_b32 s100, v254, 12
	v_readlane_b32 s101, v254, 13
	s_nop 1
	v_mov_b32_e32 v8, s100
	v_mov_b32_e32 v9, s101
	s_cbranch_vccz .Lxb2_wait
	buffer_wbl2 sc1
	s_waitcnt vmcnt(0)
	global_atomic_add v[8:9], v3, off

.LBB0_235:
	s_add_i32 s7, s17, 3
	s_cmp_ge_i32 s7, s51
	s_cbranch_scc1 .LBB0_289
	s_waitcnt vmcnt(0)
	s_waitcnt lgkmcnt(0)
	s_barrier
	s_mov_b64 s[4:5], exec
	v_readlane_b32 s8, v253, 0
	v_readlane_b32 s9, v253, 1
	s_and_b64 s[8:9], s[4:5], s[8:9]
	s_mov_b64 exec, s[8:9]
	s_cbranch_execz .LBB0_288
	s_waitcnt lgkmcnt(0)
	v_mov_b32_e32 v2, 0x20160
	ds_read2_b32 v[4:5], v2 offset1:1
	ds_read_b32 v6, v2 offset:8
	v_readlane_b32 s100, v254, 8
	v_readlane_b32 s101, v254, 9
	v_mov_b32_e32 v3, 1
	v_mov_b32_e32 v11, 0
	v_mov_b32_e32 v8, s100
	v_mov_b32_e32 v9, s101
	global_atomic_add v10, v[8:9], v3, off sc0
	s_waitcnt lgkmcnt(0)
	v_add_u32_e32 v7, 1, v6
	ds_write_b32 v2, v7 offset:8
	v_mul_lo_u32 v4, v4, v7
	v_mul_lo_u32 v5, v5, v7
	s_waitcnt vmcnt(0)
	buffer_inv sc1
	v_add_u32_e32 v10, 1, v10
	v_cmp_eq_u32_e32 vcc, v10, v4
	v_readlane_b32 s100, v254, 12
	v_readlane_b32 s101, v254, 13
	s_nop 1
	v_mov_b32_e32 v8, s100
	v_mov_b32_e32 v9, s101
	s_cbranch_vccz .Lxb3_wait
	buffer_wbl2 sc1
	s_waitcnt vmcnt(0)
	global_atomic_add v[8:9], v3, off

.LBB0_308:
	s_add_i32 s7, s17, 4
	s_cmp_ge_i32 s7, s51
	s_cbranch_scc1 .LBB0_362
	s_waitcnt vmcnt(0)
	s_waitcnt vmcnt(0) lgkmcnt(0)
	s_barrier
	s_mov_b64 s[4:5], exec
	v_readlane_b32 s8, v253, 0
	v_readlane_b32 s9, v253, 1
	s_and_b64 s[8:9], s[4:5], s[8:9]
	s_mov_b64 exec, s[8:9]
	s_cbranch_execz .LBB0_361
	s_waitcnt lgkmcnt(0)
	v_mov_b32_e32 v2, 0x20160
	ds_read2_b32 v[4:5], v2 offset1:1
	ds_read_b32 v6, v2 offset:8
	v_readlane_b32 s100, v254, 8
	v_readlane_b32 s101, v254, 9
	v_mov_b32_e32 v3, 1
	v_mov_b32_e32 v11, 0
	v_mov_b32_e32 v8, s100
	v_mov_b32_e32 v9, s101
	global_atomic_add v10, v[8:9], v3, off sc0
	s_waitcnt lgkmcnt(0)
	v_add_u32_e32 v7, 1, v6
	ds_write_b32 v2, v7 offset:8
	v_mul_lo_u32 v4, v4, v7
	v_mul_lo_u32 v5, v5, v7
	s_waitcnt vmcnt(0)
	buffer_inv sc1
	v_add_u32_e32 v10, 1, v10
	v_cmp_eq_u32_e32 vcc, v10, v4
	v_readlane_b32 s100, v254, 12
	v_readlane_b32 s101, v254, 13
	s_nop 1
	v_mov_b32_e32 v8, s100
	v_mov_b32_e32 v9, s101
	s_cbranch_vccz .Lxb4_wait
	buffer_wbl2 sc1
	s_waitcnt vmcnt(0)
	global_atomic_add v[8:9], v3, off

.LBB0_388:
	s_add_i32 s6, s17, 5
	s_cmp_ge_i32 s6, s51
	s_cbranch_scc1 .LBB0_442
	s_waitcnt vmcnt(0)
	s_waitcnt vmcnt(0)
	s_barrier
	s_mov_b64 s[4:5], exec
	v_readlane_b32 s8, v253, 0
	v_readlane_b32 s9, v253, 1
	s_and_b64 s[8:9], s[4:5], s[8:9]
	s_mov_b64 exec, s[8:9]
	s_cbranch_execz .LBB0_441
	s_waitcnt lgkmcnt(0)
	v_mov_b32_e32 v2, 0x20160
	ds_read2_b32 v[4:5], v2 offset1:1
	ds_read_b32 v6, v2 offset:8
	v_readlane_b32 s100, v254, 8
	v_readlane_b32 s101, v254, 9
	v_mov_b32_e32 v3, 1
	v_mov_b32_e32 v11, 0
	v_mov_b32_e32 v8, s100
	v_mov_b32_e32 v9, s101
	global_atomic_add v10, v[8:9], v3, off sc0
	s_waitcnt lgkmcnt(0)
	v_add_u32_e32 v7, 1, v6
	ds_write_b32 v2, v7 offset:8
	v_mul_lo_u32 v4, v4, v7
	v_mul_lo_u32 v5, v5, v7
	s_waitcnt vmcnt(0)
	buffer_inv sc1
	v_add_u32_e32 v10, 1, v10
	v_cmp_eq_u32_e32 vcc, v10, v4
	v_readlane_b32 s100, v254, 12
	v_readlane_b32 s101, v254, 13
	s_nop 1
	v_mov_b32_e32 v8, s100
	v_mov_b32_e32 v9, s101
	s_cbranch_vccz .Lxb5_wait
	buffer_wbl2 sc1
	s_waitcnt vmcnt(0)
	global_atomic_add v[8:9], v3, off

.LBB0_495:
	s_add_i32 s6, s17, 6
	s_cmp_ge_i32 s6, s51
	s_cbranch_scc1 .LBB0_549
	s_waitcnt vmcnt(0)
	s_waitcnt vmcnt(0)
	s_barrier
	s_mov_b64 s[4:5], exec
	v_readlane_b32 s8, v253, 0
	v_readlane_b32 s9, v253, 1
	s_and_b64 s[8:9], s[4:5], s[8:9]
	s_mov_b64 exec, s[8:9]
	s_cbranch_execz .LBB0_548
	s_waitcnt lgkmcnt(0)
	v_mov_b32_e32 v2, 0x20160
	ds_read2_b32 v[4:5], v2 offset1:1
	ds_read_b32 v6, v2 offset:8
	v_readlane_b32 s100, v254, 8
	v_readlane_b32 s101, v254, 9
	v_mov_b32_e32 v3, 1
	v_mov_b32_e32 v11, 0
	v_mov_b32_e32 v8, s100
	v_mov_b32_e32 v9, s101
	global_atomic_add v10, v[8:9], v3, off sc0
	s_waitcnt lgkmcnt(0)
	v_add_u32_e32 v7, 1, v6
	ds_write_b32 v2, v7 offset:8
	v_mul_lo_u32 v4, v4, v7
	v_mul_lo_u32 v5, v5, v7
	s_waitcnt vmcnt(0)
	buffer_inv sc1
	v_add_u32_e32 v10, 1, v10
	v_cmp_eq_u32_e32 vcc, v10, v4
	v_readlane_b32 s100, v254, 12
	v_readlane_b32 s101, v254, 13
	s_nop 1
	v_mov_b32_e32 v8, s100
	v_mov_b32_e32 v9, s101
	s_cbranch_vccz .Lxb6_wait
	buffer_wbl2 sc1
	s_waitcnt vmcnt(0)
	global_atomic_add v[8:9], v3, off

.LBB0_627:
	s_add_i32 s6, s17, 7
	s_cmp_ge_i32 s6, s51
	s_cbranch_scc1 .LBB0_681
	s_waitcnt vmcnt(0)
	s_waitcnt vmcnt(0)
	s_barrier
	s_mov_b64 s[4:5], exec
	v_readlane_b32 s8, v253, 0
	v_readlane_b32 s9, v253, 1
	s_and_b64 s[8:9], s[4:5], s[8:9]
	s_mov_b64 exec, s[8:9]
	s_cbranch_execz .LBB0_680
	s_waitcnt lgkmcnt(0)
	v_mov_b32_e32 v2, 0x20160
	ds_read2_b32 v[4:5], v2 offset1:1
	ds_read_b32 v6, v2 offset:8
	v_readlane_b32 s100, v254, 8
	v_readlane_b32 s101, v254, 9
	v_mov_b32_e32 v3, 1
	v_mov_b32_e32 v11, 0
	v_mov_b32_e32 v8, s100
	v_mov_b32_e32 v9, s101
	global_atomic_add v10, v[8:9], v3, off sc0
	s_waitcnt lgkmcnt(0)
	v_add_u32_e32 v7, 1, v6
	ds_write_b32 v2, v7 offset:8
	v_mul_lo_u32 v4, v4, v7
	v_mul_lo_u32 v5, v5, v7
	s_waitcnt vmcnt(0)
	buffer_inv sc1
	v_add_u32_e32 v10, 1, v10
	v_cmp_eq_u32_e32 vcc, v10, v4
	v_readlane_b32 s100, v254, 12
	v_readlane_b32 s101, v254, 13
	s_nop 1
	v_mov_b32_e32 v8, s100
	v_mov_b32_e32 v9, s101
	s_cbranch_vccz .Lxb7_wait
	buffer_wbl2 sc1
	s_waitcnt vmcnt(0)
	global_atomic_add v[8:9], v3, off

.LBB0_842:
	s_add_i32 s6, s17, 8
	s_cmp_ge_i32 s6, s51
	s_cbranch_scc1 .LBB0_896
	s_waitcnt vmcnt(0)
	s_waitcnt vmcnt(0) lgkmcnt(0)
	s_barrier
	s_mov_b64 s[4:5], exec
	v_readlane_b32 s8, v253, 0
	v_readlane_b32 s9, v253, 1
	s_and_b64 s[8:9], s[4:5], s[8:9]
	s_mov_b64 exec, s[8:9]
	s_cbranch_execz .LBB0_895
	s_waitcnt lgkmcnt(0)
	v_mov_b32_e32 v2, 0x20160
	ds_read2_b32 v[4:5], v2 offset1:1
	ds_read_b32 v6, v2 offset:8
	v_readlane_b32 s100, v254, 8
	v_readlane_b32 s101, v254, 9
	v_mov_b32_e32 v3, 1
	v_mov_b32_e32 v11, 0
	v_mov_b32_e32 v8, s100
	v_mov_b32_e32 v9, s101
	global_atomic_add v10, v[8:9], v3, off sc0
	s_waitcnt lgkmcnt(0)
	v_add_u32_e32 v7, 1, v6
	ds_write_b32 v2, v7 offset:8
	v_mul_lo_u32 v4, v4, v7
	v_mul_lo_u32 v5, v5, v7
	s_waitcnt vmcnt(0)
	buffer_inv sc1
	v_add_u32_e32 v10, 1, v10
	v_cmp_eq_u32_e32 vcc, v10, v4
	v_readlane_b32 s100, v254, 12
	v_readlane_b32 s101, v254, 13
	s_nop 1
	v_mov_b32_e32 v8, s100
	v_mov_b32_e32 v9, s101
	s_cbranch_vccz .Lxb8_wait
	buffer_wbl2 sc1
	s_waitcnt vmcnt(0)
	global_atomic_add v[8:9], v3, off

.LBB0_908:
	s_add_i32 s7, s17, 9
	s_cmp_ge_i32 s7, s51
	s_cbranch_scc1 .LBB0_962
	s_waitcnt vmcnt(0)
	s_waitcnt vmcnt(0) lgkmcnt(0)
	s_barrier
	s_mov_b64 s[4:5], exec
	v_readlane_b32 s8, v253, 0
	v_readlane_b32 s9, v253, 1
	s_and_b64 s[8:9], s[4:5], s[8:9]
	s_mov_b64 exec, s[8:9]
	s_cbranch_execz .LBB0_961
	s_waitcnt lgkmcnt(0)
	v_mov_b32_e32 v2, 0x20160
	ds_read2_b32 v[4:5], v2 offset1:1
	ds_read_b32 v6, v2 offset:8
	v_readlane_b32 s100, v254, 8
	v_readlane_b32 s101, v254, 9
	v_mov_b32_e32 v3, 1
	v_mov_b32_e32 v11, 0
	v_mov_b32_e32 v8, s100
	v_mov_b32_e32 v9, s101
	global_atomic_add v10, v[8:9], v3, off sc0
	s_waitcnt lgkmcnt(0)
	v_add_u32_e32 v7, 1, v6
	ds_write_b32 v2, v7 offset:8
	v_mul_lo_u32 v4, v4, v7
	v_mul_lo_u32 v5, v5, v7
	s_waitcnt vmcnt(0)
	buffer_inv sc1
	v_add_u32_e32 v10, 1, v10
	v_cmp_eq_u32_e32 vcc, v10, v4
	v_readlane_b32 s100, v254, 12
	v_readlane_b32 s101, v254, 13
	s_nop 1
	v_mov_b32_e32 v8, s100
	v_mov_b32_e32 v9, s101
	s_cbranch_vccz .Lxb9_wait
	buffer_wbl2 sc1
	s_waitcnt vmcnt(0)
	global_atomic_add v[8:9], v3, off

.LBB0_1020:
	s_add_i32 s6, s17, 10
	s_cmp_ge_i32 s6, s51
	s_cbranch_scc1 .LBB0_1074
	s_waitcnt vmcnt(0)
	s_waitcnt vmcnt(0) lgkmcnt(0)
	s_barrier
	s_mov_b64 s[4:5], exec
	v_readlane_b32 s8, v253, 0
	v_readlane_b32 s9, v253, 1
	s_and_b64 s[8:9], s[4:5], s[8:9]
	s_mov_b64 exec, s[8:9]
	s_cbranch_execz .LBB0_1073
	s_waitcnt lgkmcnt(0)
	v_mov_b32_e32 v2, 0x20160
	ds_read2_b32 v[4:5], v2 offset1:1
	ds_read_b32 v6, v2 offset:8
	v_readlane_b32 s100, v254, 8
	v_readlane_b32 s101, v254, 9
	v_mov_b32_e32 v3, 1
	v_mov_b32_e32 v11, 0
	v_mov_b32_e32 v8, s100
	v_mov_b32_e32 v9, s101
	global_atomic_add v10, v[8:9], v3, off sc0
	s_waitcnt lgkmcnt(0)
	v_add_u32_e32 v7, 1, v6
	ds_write_b32 v2, v7 offset:8
	v_mul_lo_u32 v4, v4, v7
	v_mul_lo_u32 v5, v5, v7
	s_waitcnt vmcnt(0)
	buffer_inv sc1
	v_add_u32_e32 v10, 1, v10
	v_cmp_eq_u32_e32 vcc, v10, v4
	v_readlane_b32 s100, v254, 12
	v_readlane_b32 s101, v254, 13
	s_nop 1
	v_mov_b32_e32 v8, s100
	v_mov_b32_e32 v9, s101
	s_cbranch_vccz .Lxb10_wait
	buffer_wbl2 sc1
	s_waitcnt vmcnt(0)
	global_atomic_add v[8:9], v3, off

.LBB0_1088:
	s_or_b64 exec, exec, s[4:5]
	s_add_i32 s6, s17, 11
	s_cmp_ge_i32 s6, s51
	s_cbranch_scc1 .LBB0_1142
	s_waitcnt vmcnt(0)
	s_waitcnt vmcnt(0) lgkmcnt(0)
	s_barrier
	s_mov_b64 s[4:5], exec
	v_readlane_b32 s8, v253, 0
	v_readlane_b32 s9, v253, 1
	s_and_b64 s[8:9], s[4:5], s[8:9]
	s_mov_b64 exec, s[8:9]
	s_cbranch_execz .LBB0_1141
	s_waitcnt lgkmcnt(0)
	v_mov_b32_e32 v2, 0x20160
	ds_read2_b32 v[4:5], v2 offset1:1
	ds_read_b32 v6, v2 offset:8
	v_readlane_b32 s100, v254, 8
	v_readlane_b32 s101, v254, 9
	v_mov_b32_e32 v3, 1
	v_mov_b32_e32 v11, 0
	v_mov_b32_e32 v8, s100
	v_mov_b32_e32 v9, s101
	global_atomic_add v10, v[8:9], v3, off sc0
	s_waitcnt lgkmcnt(0)
	v_add_u32_e32 v7, 1, v6
	ds_write_b32 v2, v7 offset:8
	v_mul_lo_u32 v4, v4, v7
	v_mul_lo_u32 v5, v5, v7
	s_waitcnt vmcnt(0)
	buffer_inv sc1
	v_add_u32_e32 v10, 1, v10
	v_cmp_eq_u32_e32 vcc, v10, v4
	v_readlane_b32 s100, v254, 12
	v_readlane_b32 s101, v254, 13
	s_nop 1
	v_mov_b32_e32 v8, s100
	v_mov_b32_e32 v9, s101
	s_cbranch_vccz .Lxb11_wait
	buffer_wbl2 sc1
	s_waitcnt vmcnt(0)
	global_atomic_add v[8:9], v3, off
